# v2 plus RG-LRU chunk loop: do not wait for the MRG store ack at the chunk end (vmcnt 1 to 2)
# speedup vs baseline: 1.0071x; 1.0019x over previous
; __device__ __forceinline__ unsigned cvt_pk_bf16_pure(float lo, float hi) { unsigned r; asm("v_cvt_pk_bf16_f32 %0, %1, %2" : "=v"(r) : "v"(lo), "v"(hi)); return r; }
; __device__ __forceinline__ void lru_item(const Args& a, LAS unsigned char* lds, bool sample, int b, int head, int q, int tid, int lane, int wave) {
;     ...
;     const int ch0 = 64 * head + 16 * q;
;     const int fr = lane & 15, fq = lane >> 4;
;     bf16x8 Bf[2][2];
; #pragma unroll
;     for (int mat = 0; mat < 2; ++mat)
; #pragma unroll
;         for (int ks = 0; ks < 2; ++ks) {
;             const float* w = (mat ? a.in[I_WX] : a.in[I_WA]) + ((size_t)(head * 64 + 32 * ks + 8 * fq)) * 64 + 16 * q + fr;
;             u32x4 p; p.x = cvt_pk_bf16_pure(w[0], w[64]); p.y = cvt_pk_bf16_pure(w[128], w[192]); p.z = cvt_pk_bf16_pure(w[256], w[320]); p.w = cvt_pk_bf16_pure(w[384], w[448]);
;             Bf[mat][ks] = __builtin_bit_cast(bf16x8, p);
;         }
;     const int chn = ch0 + fr;
;     const float ba = a.in[I_BA][chn], bx_ = a.in[I_BX][chn], laml = a.in[I_LAML][chn];
;     const int cq = tid & 15, cch = 64 * head + 4 * cq, rg = tid >> 4;
;     const f32x4 cw0 = *(const f32x4*)(a.in[I_CONVW] + cch), cw1 = *(const f32x4*)(a.in[I_CONVW] + DH + cch), cw2 = *(const f32x4*)(a.in[I_CONVW] + 2 * DH + cch),
;                 cw3 = *(const f32x4*)(a.in[I_CONVW] + 3 * DH + cch), cb = *(const f32x4*)(a.in[I_CONVB] + cch);
;     const int er = tid >> 1, eh = tid & 1;
;     f32x4 xin[11]; u32x4 ggn;
;     if (!sample) {
;         const int R0 = b * SEQ, r0 = rg * 8;
; #pragma unroll
;         for (int i = 0; i < 11; ++i) { const int t = r0 + i - 3; xin[i] = *(const f32x4*)(XL + (size_t)(R0 + (t >= 0 ? t : 0)) * DH + cch); }
;         ggn = *(const u32x4*)(GG + (size_t)(R0 + er) * DH + ch0 + 8 * eh);
.LBB0_671:
	s_lshl_b32 s30, s70, 1
	s_bfe_u32 s9, s70, 0x10005
	s_bfe_u32 s8, s70, 0x20003
	s_and_b32 s30, s30, 14
	s_or_b32 s37, s30, s9
	s_lshl_b32 s30, s8, 6
	v_lshl_or_b32 v2, s37, 14, v170
	v_mov_b32_e32 v3, v99
	v_lshl_add_u64 v[4:5], v[100:101], 0, s[30:31]
	v_lshl_add_u64 v[6:7], v[4:5], 0, v[2:3]
	global_load_dword v8, v[6:7], off
	global_load_dword v9, v[6:7], off offset:256
	global_load_dword v10, v[6:7], off offset:512
	global_load_dword v11, v[6:7], off offset:768
	global_load_dword v12, v[6:7], off offset:1024
	global_load_dword v13, v[6:7], off offset:1280
	global_load_dword v14, v[6:7], off offset:1536
	global_load_dword v15, v[6:7], off offset:1792
	v_or_b32_e32 v6, 0x2000, v2
	v_mov_b32_e32 v7, v99
	v_lshl_add_u64 v[4:5], v[4:5], 0, v[6:7]
	global_load_dword v16, v[4:5], off
	global_load_dword v17, v[4:5], off offset:256
	global_load_dword v40, v[4:5], off offset:512
	global_load_dword v41, v[4:5], off offset:768
	global_load_dword v42, v[4:5], off offset:1024
	global_load_dword v43, v[4:5], off offset:1280
	global_load_dword v44, v[4:5], off offset:1536
	global_load_dword v45, v[4:5], off offset:1792
	v_lshl_add_u64 v[4:5], v[102:103], 0, s[30:31]
	v_lshl_add_u64 v[2:3], v[4:5], 0, v[2:3]
	global_load_dword v46, v[2:3], off
	global_load_dword v47, v[2:3], off offset:256
	global_load_dword v48, v[2:3], off offset:512
	global_load_dword v49, v[2:3], off offset:768
	global_load_dword v50, v[2:3], off offset:1024
	global_load_dword v51, v[2:3], off offset:1280
	global_load_dword v52, v[2:3], off offset:1536
	global_load_dword v53, v[2:3], off offset:1792
	s_lshl_b32 s30, s12, 7
	s_lshl_b32 s9, s9, 7
	s_and_b32 s30, s30, 0x700
	s_lshl_b32 s36, s8, 5
	s_or_b32 s9, s30, s9
	s_lshl_b32 s45, s8, 4
	s_or_b32 s36, s36, s9
	s_lshl_b32 s9, s37, 6
	v_lshl_add_u64 v[2:3], v[4:5], 0, v[6:7]
	s_or_b32 s71, s9, s45
	global_load_dword v54, v[2:3], off
	global_load_dword v55, v[2:3], off offset:256
	global_load_dword v56, v[2:3], off offset:512
	global_load_dword v57, v[2:3], off offset:768
	global_load_dword v58, v[2:3], off offset:1024
	global_load_dword v59, v[2:3], off offset:1280
	global_load_dword v60, v[2:3], off offset:1536
	global_load_dword v61, v[2:3], off offset:1792
	v_or_b32_e32 v2, s9, v96
	v_or_b32_e32 v3, s71, v90
	v_readlane_b32 s48, v254, 47
	v_lshlrev_b32_e32 v38, 2, v2
	v_lshlrev_b32_e32 v2, 2, v3
	v_readlane_b32 s50, v254, 49
	v_readlane_b32 s51, v254, 50
	global_load_dwordx4 v[26:29], v38, s[4:5]
	global_load_dwordx4 v[22:25], v38, s[20:21]
	global_load_dwordx4 v[18:21], v38, s[22:23]
	v_readlane_b32 s54, v254, 53
	v_readlane_b32 s55, v254, 54
	v_readlane_b32 s56, v254, 55
	v_readlane_b32 s57, v254, 56
	global_load_dword v97, v2, s[50:51]
	s_nop 1
	global_load_dword v93, v2, s[54:55]
	s_nop 0
	global_load_dword v86, v2, s[56:57]
	v_readlane_b32 s49, v254, 48
	v_readlane_b32 s52, v254, 51
	v_readlane_b32 s53, v254, 52
	v_readlane_b32 s58, v254, 57
	v_readlane_b32 s59, v254, 58
	v_readlane_b32 s60, v254, 59
	v_readlane_b32 s61, v254, 60
	v_readlane_b32 s62, v254, 61
	v_readlane_b32 s63, v254, 62
	v_readlane_b32 s48, v254, 20
	s_ashr_i32 s44, s70, 6
	v_readlane_b32 s49, v254, 21
	v_readlane_b32 s50, v254, 22
	v_readlane_b32 s51, v254, 23
	v_readlane_b32 s60, v254, 32
	v_readlane_b32 s61, v254, 33
	v_mov_b32_e32 v39, v99
	v_readlane_b32 s62, v254, 34
	v_readlane_b32 s63, v254, 35
	s_mov_b64 s[48:49], s[60:61]
	s_lshl_b32 s72, s44, 11
	s_mov_b64 s[50:51], s[62:63]
	global_load_dwordx4 v[30:33], v38, s[48:49]
	global_load_dwordx4 v[34:37], v38, s[50:51]
	v_lshl_add_u64 v[110:111], s[10:11], 0, v[38:39]
	v_or_b32_e32 v38, s72, v91
	v_ashrrev_i32_e32 v39, 31, v38
	v_lshlrev_b64 v[38:39], 12, v[38:39]
	v_lshl_add_u64 v[38:39], v[110:111], 0, v[38:39]
	v_readlane_b32 s46, v254, 63
	v_readlane_b32 s47, v253, 0
	s_lshl_b32 s30, s71, 1
	v_cmp_eq_u32_e64 s[8:9], s8, v136
	v_or_b32_e32 v181, s72, v171
	v_or_b32_e32 v182, s72, v172
	v_readlane_b32 s52, v254, 24
	v_readlane_b32 s53, v254, 25
	v_readlane_b32 s54, v254, 26
	s_waitcnt vmcnt(38)
	v_cvt_pk_bf16_f32 v2, v8, v9
	s_waitcnt vmcnt(32)
	v_cvt_pk_bf16_f32 v5, v14, v15
	s_waitcnt vmcnt(28)
	v_cvt_pk_bf16_f32 v15, v40, v41
	v_or_b32_e32 v40, s72, v134
	v_ashrrev_i32_e32 v41, 31, v40
	v_lshlrev_b64 v[40:41], 12, v[40:41]
	v_cvt_pk_bf16_f32 v3, v10, v11
	s_waitcnt vmcnt(18)
	v_cvt_pk_bf16_f32 v8, v50, v51
	s_waitcnt vmcnt(16)
	v_cvt_pk_bf16_f32 v9, v52, v53
	s_waitcnt vmcnt(14)
	v_cvt_pk_bf16_f32 v10, v54, v55
	v_lshl_add_u64 v[40:41], v[110:111], 0, v[40:41]
	global_load_dwordx4 v[50:53], v[38:39], off
	global_load_dwordx4 v[82:85], v[40:41], off
	v_or_b32_e32 v38, s72, v135
	v_or_b32_e32 v54, s72, v1
	v_ashrrev_i32_e32 v39, 31, v38
	v_ashrrev_i32_e32 v55, 31, v54
	v_lshlrev_b64 v[38:39], 12, v[38:39]
	v_lshlrev_b64 v[40:41], 12, v[54:55]
	v_lshl_add_u64 v[38:39], v[110:111], 0, v[38:39]
	v_lshl_add_u64 v[40:41], v[110:111], 0, v[40:41]
	global_load_dwordx4 v[78:81], v[38:39], off
	global_load_dwordx4 v[70:73], v[40:41], off
	v_or_b32_e32 v38, 1, v54
	v_or_b32_e32 v40, 2, v54
	v_ashrrev_i32_e32 v39, 31, v38
	v_ashrrev_i32_e32 v41, 31, v40
	s_waitcnt vmcnt(16)
	v_cvt_pk_bf16_f32 v11, v56, v57
	v_lshlrev_b64 v[38:39], 12, v[38:39]
	v_lshlrev_b64 v[40:41], 12, v[40:41]
	v_or_b32_e32 v56, s72, v162
	v_lshl_add_u64 v[38:39], v[110:111], 0, v[38:39]
	v_lshl_add_u64 v[40:41], v[110:111], 0, v[40:41]
	v_ashrrev_i32_e32 v57, 31, v56
	s_waitcnt vmcnt(6)
; __device__ __forceinline__ void lru_item(const Args& a, LAS unsigned char* lds, bool sample, int b, int head, int q, int tid, int lane, int wave) {
;     ...
;         for (int i = 0; i < 11; ++i) { const int t = r0 + i - 3; xin[i] = *(const f32x4*)(XL + (size_t)(R0 + (t >= 0 ? t : 0)) * DH + cch); }
;         ggn = *(const u32x4*)(GG + (size_t)(R0 + er) * DH + ch0 + 8 * eh);
;     }
;     const float spl = log1pf(expf(-laml));
;     if (!sample) {
;         float hcar = 0.f;
;         if (rg == 0) { xin[0] = (f32x4){0.f, 0.f, 0.f, 0.f}; xin[1] = xin[0]; xin[2] = xin[0]; }
	v_mul_f32_e32 v74, 0xbfb8aa3b, v86
	v_cvt_pk_bf16_f32 v14, v16, v17
	v_cvt_pk_bf16_f32 v16, v42, v43
	v_cvt_pk_bf16_f32 v17, v44, v45
	global_load_dwordx4 v[66:69], v[38:39], off
	global_load_dwordx4 v[62:65], v[40:41], off
	v_or_b32_e32 v38, 3, v54
	v_or_b32_e32 v40, 4, v54
	v_or_b32_e32 v42, 5, v54
	v_or_b32_e32 v44, 6, v54
	v_or_b32_e32 v54, 7, v54
	v_lshlrev_b64 v[56:57], 11, v[56:57]
	v_fma_f32 v75, v86, s28, -v74
	v_rndne_f32_e32 v76, v74
	v_ashrrev_i32_e32 v39, 31, v38
	v_ashrrev_i32_e32 v41, 31, v40
	v_ashrrev_i32_e32 v43, 31, v42
	v_ashrrev_i32_e32 v45, 31, v44
	v_ashrrev_i32_e32 v55, 31, v54
	v_lshl_add_u64 v[56:57], s[46:47], 0, v[56:57]
	v_fmac_f32_e32 v75, 0xb2a5705f, v86
	v_sub_f32_e32 v74, v74, v76
	v_lshlrev_b64 v[38:39], 12, v[38:39]
	v_lshlrev_b64 v[40:41], 12, v[40:41]
	v_lshlrev_b64 v[42:43], 12, v[42:43]
	v_lshlrev_b64 v[44:45], 12, v[44:45]
	v_lshlrev_b64 v[54:55], 12, v[54:55]
	v_lshl_add_u64 v[56:57], v[56:57], 0, s[30:31]
	v_add_f32_e32 v74, v74, v75
	v_lshl_add_u64 v[38:39], v[110:111], 0, v[38:39]
	v_lshl_add_u64 v[40:41], v[110:111], 0, v[40:41]
	v_lshl_add_u64 v[42:43], v[110:111], 0, v[42:43]
	v_lshl_add_u64 v[44:45], v[110:111], 0, v[44:45]
	v_lshl_add_u64 v[54:55], v[110:111], 0, v[54:55]
	v_exp_f32_e32 v87, v74
	v_lshl_add_u64 v[74:75], v[56:57], 0, v[98:99]
	v_cvt_pk_bf16_f32 v4, v12, v13
	v_cvt_pk_bf16_f32 v6, v46, v47
	v_cvt_pk_bf16_f32 v7, v48, v49
	v_cvt_pk_bf16_f32 v12, v58, v59
	v_cvt_pk_bf16_f32 v13, v60, v61
	global_load_dwordx4 v[58:61], v[38:39], off
	s_nop 0
	global_load_dwordx4 v[38:41], v[40:41], off
	s_nop 0
	global_load_dwordx4 v[46:49], v[42:43], off
	s_nop 0
	global_load_dwordx4 v[42:45], v[44:45], off
	v_cvt_i32_f32_e32 v88, v76
	global_load_dwordx4 v[54:57], v[54:55], off
	s_nop 0
	global_load_dwordx4 v[74:77], v[74:75], off
	v_cmp_nlt_f32_e32 vcc, s29, v86
	v_readlane_b32 s55, v254, 27
	v_ldexp_f32 v87, v87, v88
	v_cndmask_b32_e32 v87, 0, v87, vcc
	v_cmp_ngt_f32_e32 vcc, s33, v86
	v_readlane_b32 s56, v254, 28
	v_readlane_b32 s57, v254, 29
	v_cndmask_b32_e32 v88, v174, v87, vcc
	v_add_f32_e32 v89, 1.0, v88
	v_add_f32_e32 v86, -1.0, v89
	v_sub_f32_e32 v87, v86, v89
	v_add_f32_e32 v87, 1.0, v87
	v_sub_f32_e32 v86, v88, v86
	v_add_f32_e32 v108, v86, v87
	v_frexp_mant_f32_e32 v109, v89
	v_cvt_f64_f32_e32 v[86:87], v89
	v_frexp_exp_i32_f64_e32 v86, v[86:87]
	v_cmp_gt_f32_e32 vcc, s35, v109
	s_waitcnt vmcnt(10)
	v_cndmask_b32_e64 v85, v85, 0, s[0:1]
	v_cndmask_b32_e64 v84, v84, 0, s[0:1]
	v_subbrev_co_u32_e32 v86, vcc, 0, v86, vcc
	v_sub_u32_e32 v87, 0, v86
	v_ldexp_f32 v89, v89, v87
	v_ldexp_f32 v87, v108, v87
	v_add_f32_e32 v108, -1.0, v89
	v_add_f32_e32 v113, 1.0, v89
	v_add_f32_e32 v109, 1.0, v108
	v_add_f32_e32 v114, -1.0, v113
	v_sub_f32_e32 v109, v89, v109
	v_sub_f32_e32 v89, v89, v114
	v_add_f32_e32 v109, v87, v109
	v_add_f32_e32 v87, v87, v89
	v_add_f32_e32 v89, v113, v87
	v_rcp_f32_e32 v114, v89
	v_add_f32_e32 v112, v108, v109
	v_sub_f32_e32 v108, v108, v112
	v_add_f32_e32 v108, v109, v108
	v_sub_f32_e32 v109, v113, v89
	v_add_f32_e32 v87, v87, v109
	v_mul_f32_e32 v109, v112, v114
	v_mul_f32_e32 v113, v89, v109
	v_fma_f32 v115, v109, v89, -v113
	v_fmac_f32_e32 v115, v109, v87
	v_add_f32_e32 v116, v113, v115
	v_sub_f32_e32 v117, v112, v116
	v_sub_f32_e32 v112, v112, v117
	v_sub_f32_e32 v113, v116, v113
	v_sub_f32_e32 v112, v112, v116
	v_add_f32_e32 v108, v108, v112
	v_sub_f32_e32 v112, v113, v115
	v_add_f32_e32 v108, v112, v108
	v_add_f32_e32 v112, v117, v108
	v_mul_f32_e32 v113, v114, v112
	v_mul_f32_e32 v115, v89, v113
	v_fma_f32 v89, v113, v89, -v115
	v_fmac_f32_e32 v89, v113, v87
	v_sub_f32_e32 v87, v117, v112
	v_add_f32_e32 v87, v108, v87
	v_add_f32_e32 v108, v115, v89
	v_sub_f32_e32 v116, v112, v108
	v_sub_f32_e32 v112, v112, v116
	v_sub_f32_e32 v115, v108, v115
	v_sub_f32_e32 v108, v112, v108
	v_add_f32_e32 v87, v87, v108
	v_sub_f32_e32 v89, v115, v89
	v_cvt_f32_i32_e32 v86, v86
	v_add_f32_e32 v87, v89, v87
	v_add_f32_e32 v89, v109, v113
	v_add_f32_e32 v87, v116, v87
	v_sub_f32_e32 v108, v89, v109
	v_mul_f32_e32 v87, v114, v87
	v_sub_f32_e32 v108, v113, v108
	v_add_f32_e32 v87, v108, v87
	v_mul_f32_e32 v113, 0x3f317218, v86
	v_add_f32_e32 v108, v89, v87
	v_fma_f32 v114, v86, s68, -v113
	v_mul_f32_e32 v109, v108, v108
	v_fmac_f32_e32 v114, 0xb102e308, v86
	v_sub_f32_e32 v86, v108, v89
	v_fmamk_f32 v112, v109, 0x3e9b6dac, v173
	v_sub_f32_e32 v86, v87, v86
	v_add_f32_e32 v87, v113, v114
	v_fmaak_f32 v112, v109, v112, 0x3f2aaada
	v_sub_f32_e32 v89, v87, v113
	v_ldexp_f32 v113, v108, 1
	v_mul_f32_e32 v108, v108, v109
	v_mul_f32_e32 v108, v108, v112
	v_add_f32_e32 v109, v113, v108
	v_sub_f32_e32 v112, v109, v113
	v_ldexp_f32 v86, v86, 1
	v_sub_f32_e32 v108, v108, v112
	v_add_f32_e32 v86, v86, v108
	v_add_f32_e32 v108, v109, v86
	v_sub_f32_e32 v109, v108, v109
	v_sub_f32_e32 v86, v86, v109
	v_add_f32_e32 v109, v87, v108
	v_sub_f32_e32 v112, v109, v87
	v_sub_f32_e32 v113, v109, v112
	v_sub_f32_e32 v89, v114, v89
	v_sub_f32_e32 v87, v87, v113
	v_sub_f32_e32 v108, v108, v112
	v_add_f32_e32 v87, v108, v87
	v_add_f32_e32 v108, v89, v86
	v_sub_f32_e32 v112, v108, v89
	v_sub_f32_e32 v113, v108, v112
	v_sub_f32_e32 v89, v89, v113
	v_sub_f32_e32 v86, v86, v112
	v_add_f32_e32 v87, v108, v87
	v_add_f32_e32 v86, v86, v89
	v_add_f32_e32 v89, v109, v87
	v_sub_f32_e32 v108, v89, v109
	v_sub_f32_e32 v87, v87, v108
	v_add_f32_e32 v86, v86, v87
	v_add_f32_e32 v86, v89, v86
	v_cmp_neq_f32_e32 vcc, s34, v88
	v_lshl_add_u64 v[112:113], v[104:105], 0, s[30:31]
	s_ashr_i32 s30, s72, 31
	v_cndmask_b32_e32 v86, v174, v86, vcc
	v_cmp_lt_f32_e64 vcc, |v88|, s69
	v_cndmask_b32_e64 v87, v51, 0, s[0:1]
	v_mov_b32_e32 v51, s30
	v_cndmask_b32_e32 v180, v86, v88, vcc
	v_cndmask_b32_e64 v86, v50, 0, s[0:1]
	v_or_b32_e32 v50, s72, v162
	v_lshl_add_u64 v[114:115], v[50:51], 2, s[96:97]
	v_lshlrev_b64 v[50:51], 12, v[50:51]
	v_or_b32_e32 v50, s36, v50
	s_waitcnt vmcnt(1)
	v_cndmask_b32_e64 v81, v81, 0, s[0:1]
	v_cndmask_b32_e64 v80, v80, 0, s[0:1]
	v_cndmask_b32_e64 v79, v79, 0, s[0:1]
	v_cndmask_b32_e64 v78, v78, 0, s[0:1]
	v_cndmask_b32_e64 v83, v83, 0, s[0:1]
	v_cndmask_b32_e64 v82, v82, 0, s[0:1]
	v_cndmask_b32_e64 v89, v53, 0, s[0:1]
	v_cndmask_b32_e64 v88, v52, 0, s[0:1]
	v_lshl_add_u64 v[116:117], v[106:107], 0, v[50:51]
	s_mov_b32 s30, 0
	v_mov_b32_e32 v109, 0
	v_readlane_b32 s58, v254, 30
	v_readlane_b32 s59, v254, 31
; #define LAS __attribute__((address_space(3)))
; __device__ __forceinline__ unsigned cvt_pk_bf16(float lo, float hi) { unsigned r; asm("v_cvt_pk_bf16_f32 %0, %1, %2" : "=v"(r) : "v"(lo), "v"(hi)); return r; }
; __device__ __forceinline__ void lru_item(const Args& a, LAS unsigned char* lds, bool sample, int b, int head, int q, int tid, int lane, int wave) {
;     ...
;         for (int chk = 0; chk < 8; ++chk) {
;             const int R0 = b * SEQ + chk * 256, r0 = rg * 8;
; #pragma unroll
;             for (int rr = 0; rr < 8; ++rr) {
;                 const f32x4 xc = cb + cw0 * xin[rr] + cw1 * xin[rr + 1] + cw2 * xin[rr + 2] + cw3 * xin[rr + 3];
;                 u32x2 w; w.x = cvt_pk_bf16(xc[0], xc[1]); w.y = cvt_pk_bf16(xc[2], xc[3]);
;                 *(LAS u32x2*)(XC + (r0 + rr) * XC_PITCH + 8 * cq) = w;
;                 if ((cq >> 2) == q) *(LAS f32x4*)(XCF + (r0 + rr) * 16 + 4 * (cq & 3)) = xc;
;             }
.LBB0_672:
	v_pk_fma_f32 v[50:51], v[32:33], v[88:89], v[36:37]
	v_pk_fma_f32 v[52:53], v[30:31], v[86:87], v[34:35]
	v_pk_fma_f32 v[50:51], v[28:29], v[84:85], v[50:51]
	v_pk_fma_f32 v[52:53], v[26:27], v[82:83], v[52:53]
	v_pk_fma_f32 v[50:51], v[24:25], v[80:81], v[50:51]
	v_pk_fma_f32 v[86:87], v[22:23], v[78:79], v[52:53]
	s_waitcnt vmcnt(8)
	v_pk_fma_f32 v[52:53], v[20:21], v[72:73], v[50:51]
	v_pk_fma_f32 v[50:51], v[18:19], v[70:71], v[86:87]
	v_cvt_pk_bf16_f32 v87, v52, v53
	s_nop 0
	v_cvt_pk_bf16_f32 v86, v50, v51
	ds_write_b64 v175, v[86:87]
	s_and_saveexec_b64 s[36:37], s[8:9]
	v_add_u32_e32 v86, v137, v138
	ds_write_b128 v86, v[50:53] offset:36864
	s_or_b64 exec, exec, s[36:37]
	v_pk_fma_f32 v[50:51], v[32:33], v[84:85], v[36:37]
	v_pk_fma_f32 v[52:53], v[30:31], v[82:83], v[34:35]
	v_pk_fma_f32 v[50:51], v[28:29], v[80:81], v[50:51]
	v_pk_fma_f32 v[52:53], v[26:27], v[78:79], v[52:53]
	v_pk_fma_f32 v[50:51], v[24:25], v[72:73], v[50:51]
	v_pk_fma_f32 v[82:83], v[22:23], v[70:71], v[52:53]
	s_waitcnt vmcnt(7)
	v_pk_fma_f32 v[52:53], v[20:21], v[68:69], v[50:51]
	v_pk_fma_f32 v[50:51], v[18:19], v[66:67], v[82:83]
	v_cvt_pk_bf16_f32 v83, v52, v53
	s_nop 0
	v_cvt_pk_bf16_f32 v82, v50, v51
	ds_write_b64 v176, v[82:83]
	s_and_saveexec_b64 s[36:37], s[8:9]
	v_add_u32_e32 v82, v137, v148
	ds_write_b128 v82, v[50:53] offset:36864
	s_or_b64 exec, exec, s[36:37]
	v_pk_fma_f32 v[50:51], v[32:33], v[80:81], v[36:37]
	v_pk_fma_f32 v[52:53], v[30:31], v[78:79], v[34:35]
	v_pk_fma_f32 v[50:51], v[28:29], v[72:73], v[50:51]
	v_pk_fma_f32 v[52:53], v[26:27], v[70:71], v[52:53]
	v_pk_fma_f32 v[50:51], v[24:25], v[68:69], v[50:51]
	v_pk_fma_f32 v[78:79], v[22:23], v[66:67], v[52:53]
	s_waitcnt vmcnt(6)
	v_pk_fma_f32 v[52:53], v[20:21], v[64:65], v[50:51]
	v_pk_fma_f32 v[50:51], v[18:19], v[62:63], v[78:79]
	v_cvt_pk_bf16_f32 v79, v52, v53
	s_nop 0
	v_cvt_pk_bf16_f32 v78, v50, v51
	ds_write_b64 v176, v[78:79] offset:144
	s_and_saveexec_b64 s[36:37], s[8:9]
	v_add_u32_e32 v78, v137, v149
	ds_write_b128 v78, v[50:53] offset:36864
	s_or_b64 exec, exec, s[36:37]
	v_pk_fma_f32 v[50:51], v[32:33], v[72:73], v[36:37]
	v_pk_fma_f32 v[52:53], v[30:31], v[70:71], v[34:35]
	v_pk_fma_f32 v[50:51], v[28:29], v[68:69], v[50:51]
	v_pk_fma_f32 v[52:53], v[26:27], v[66:67], v[52:53]
	v_pk_fma_f32 v[50:51], v[24:25], v[64:65], v[50:51]
	v_pk_fma_f32 v[70:71], v[22:23], v[62:63], v[52:53]
	s_waitcnt vmcnt(5)
	v_pk_fma_f32 v[52:53], v[20:21], v[60:61], v[50:51]
	v_pk_fma_f32 v[50:51], v[18:19], v[58:59], v[70:71]
	v_cvt_pk_bf16_f32 v71, v52, v53
	s_nop 0
	v_cvt_pk_bf16_f32 v70, v50, v51
	ds_write_b64 v176, v[70:71] offset:288
	s_and_saveexec_b64 s[36:37], s[8:9]
	v_add_u32_e32 v70, v137, v150
	ds_write_b128 v70, v[50:53] offset:36864
	s_or_b64 exec, exec, s[36:37]
	v_pk_fma_f32 v[50:51], v[32:33], v[68:69], v[36:37]
	v_pk_fma_f32 v[52:53], v[30:31], v[66:67], v[34:35]
	v_pk_fma_f32 v[50:51], v[28:29], v[64:65], v[50:51]
	v_pk_fma_f32 v[52:53], v[26:27], v[62:63], v[52:53]
	v_pk_fma_f32 v[50:51], v[24:25], v[60:61], v[50:51]
	v_pk_fma_f32 v[66:67], v[22:23], v[58:59], v[52:53]
	s_waitcnt vmcnt(4)
	v_pk_fma_f32 v[52:53], v[20:21], v[40:41], v[50:51]
	v_pk_fma_f32 v[50:51], v[18:19], v[38:39], v[66:67]
	v_cvt_pk_bf16_f32 v67, v52, v53
	s_nop 0
	v_cvt_pk_bf16_f32 v66, v50, v51
	ds_write_b64 v176, v[66:67] offset:432
	s_and_saveexec_b64 s[36:37], s[8:9]
	v_add_u32_e32 v66, v137, v151
	ds_write_b128 v66, v[50:53] offset:36864
	s_or_b64 exec, exec, s[36:37]
	v_pk_fma_f32 v[50:51], v[32:33], v[64:65], v[36:37]
	v_pk_fma_f32 v[52:53], v[30:31], v[62:63], v[34:35]
	v_pk_fma_f32 v[50:51], v[28:29], v[60:61], v[50:51]
	v_pk_fma_f32 v[52:53], v[26:27], v[58:59], v[52:53]
	v_pk_fma_f32 v[50:51], v[24:25], v[40:41], v[50:51]
	v_pk_fma_f32 v[62:63], v[22:23], v[38:39], v[52:53]
	s_waitcnt vmcnt(3)
	v_pk_fma_f32 v[52:53], v[20:21], v[48:49], v[50:51]
	v_pk_fma_f32 v[50:51], v[18:19], v[46:47], v[62:63]
	v_cvt_pk_bf16_f32 v63, v52, v53
	s_nop 0
	v_cvt_pk_bf16_f32 v62, v50, v51
	ds_write_b64 v176, v[62:63] offset:576
	s_and_saveexec_b64 s[36:37], s[8:9]
	v_add_u32_e32 v62, v137, v152
	ds_write_b128 v62, v[50:53] offset:36864
	s_or_b64 exec, exec, s[36:37]
	v_pk_fma_f32 v[50:51], v[32:33], v[60:61], v[36:37]
	v_pk_fma_f32 v[52:53], v[30:31], v[58:59], v[34:35]
	v_pk_fma_f32 v[50:51], v[28:29], v[40:41], v[50:51]
	v_pk_fma_f32 v[52:53], v[26:27], v[38:39], v[52:53]
	v_pk_fma_f32 v[50:51], v[24:25], v[48:49], v[50:51]
	v_pk_fma_f32 v[58:59], v[22:23], v[46:47], v[52:53]
	s_waitcnt vmcnt(2)
	v_pk_fma_f32 v[52:53], v[20:21], v[44:45], v[50:51]
	v_pk_fma_f32 v[50:51], v[18:19], v[42:43], v[58:59]
	v_cvt_pk_bf16_f32 v59, v52, v53
	s_nop 0
	v_cvt_pk_bf16_f32 v58, v50, v51
	ds_write_b64 v176, v[58:59] offset:720
	s_and_saveexec_b64 s[36:37], s[8:9]
	v_add_u32_e32 v58, v137, v153
	ds_write_b128 v58, v[50:53] offset:36864
	s_or_b64 exec, exec, s[36:37]
	v_pk_fma_f32 v[40:41], v[32:33], v[40:41], v[36:37]
	v_pk_fma_f32 v[38:39], v[30:31], v[38:39], v[34:35]
	v_pk_fma_f32 v[40:41], v[28:29], v[48:49], v[40:41]
	v_pk_fma_f32 v[38:39], v[26:27], v[46:47], v[38:39]
	v_pk_fma_f32 v[40:41], v[24:25], v[44:45], v[40:41]
	v_pk_fma_f32 v[38:39], v[22:23], v[42:43], v[38:39]
	s_waitcnt vmcnt(2)
; #define LAS __attribute__((address_space(3)))
; __device__ __forceinline__ float fexp(float x) { return __builtin_amdgcn_exp2f(x * 1.44269504089f); }
; __device__ __forceinline__ float fsigmoid(float x) { return __builtin_amdgcn_rcpf(1.0f + fexp(-x)); }
; __device__ __forceinline__ void lru_item(const Args& a, LAS unsigned char* lds, bool sample, int b, int head, int q, int tid, int lane, int wave) {
;     ...
;             const u32x4 gw = ggn;
;             if (chk < 7) {
;                 const float* p = XL + (size_t)(R0 + 256 + r0 - 3) * DH + cch;
; #pragma unroll
;                 for (int i = 0; i < 11; ++i) xin[i] = *(const f32x4*)(p + (size_t)i * DH);
;                 ggn = *(const u32x4*)(GG + (size_t)(R0 + 256 + er) * DH + ch0 + 8 * eh);
;             }
;             __syncthreads();
; #pragma unroll
;             for (int tt = 0; tt < 2; ++tt) {
;                 const int tile = 2 * wave + tt;
;                 f32x4 ar = (f32x4){0.f, 0.f, 0.f, 0.f}, ax = ar;
; #pragma unroll
;                 for (int ks = 0; ks < 2; ++ks) {
;                     const bf16x8 af = *(const LAS bf16x8*)(XC + (16 * tile + fr) * XC_PITCH + 64 * ks + 16 * fq);
;                     ar = __builtin_amdgcn_mfma_f32_16x16x32_bf16(af, Bf[0][ks], ar, 0, 0, 0);
;                     ax = __builtin_amdgcn_mfma_f32_16x16x32_bf16(af, Bf[1][ks], ax, 0, 0, 0);
;                 }
; #pragma unroll
;                 for (int r4 = 0; r4 < 4; ++r4) {
;                     const int rr = 16 * tile + 4 * fq + r4;
;                     const float xcv = XCF[rr * 16 + fr];
;                     const float rg_ = fsigmoid(ar[r4] + ba), ig = fsigmoid(ax[r4] + bx_);
;                     const float la = -8.0f * rg_ * spl;
;                     const float av = fexp(la); AA[rr * 16 + fr] = av; BX[rr * 16 + fr] = __builtin_amdgcn_sqrtf(fmaxf(fmaf(-av, av, 1.0f), 0.f)) * (ig * xcv);
;                 }
;             }
	v_pk_fma_f32 v[40:41], v[20:21], v[56:57], v[40:41]
	v_pk_fma_f32 v[38:39], v[18:19], v[54:55], v[38:39]
	v_cvt_pk_bf16_f32 v43, v40, v41
	s_nop 0
	v_cvt_pk_bf16_f32 v42, v38, v39
	ds_write_b64 v176, v[42:43] offset:864
	s_and_saveexec_b64 s[36:37], s[8:9]
	v_add_u32_e32 v42, v137, v154
	ds_write_b128 v42, v[38:41] offset:36864
	s_or_b64 exec, exec, s[36:37]
	v_add_u32_e32 v38, s30, v182
	v_ashrrev_i32_e32 v39, 31, v38
	v_lshlrev_b64 v[38:39], 12, v[38:39]
	v_lshl_add_u64 v[50:51], v[110:111], 0, v[38:39]
	v_add_co_u32_e32 v38, vcc, 0x1000, v50
	v_add_u32_e32 v52, s30, v181
	s_nop 0
	v_addc_co_u32_e32 v39, vcc, 0, v51, vcc
	global_load_dwordx4 v[86:89], v[50:51], off
	global_load_dwordx4 v[82:85], v[38:39], off
	v_add_co_u32_e32 v38, vcc, 0x2000, v50
	v_ashrrev_i32_e32 v53, 31, v52
	s_nop 0
	v_addc_co_u32_e32 v39, vcc, 0, v51, vcc
	v_add_co_u32_e32 v40, vcc, 0x3000, v50
	v_lshlrev_b64 v[52:53], 11, v[52:53]
	s_nop 0
	v_addc_co_u32_e32 v41, vcc, 0, v51, vcc
	global_load_dwordx4 v[78:81], v[38:39], off
	global_load_dwordx4 v[70:73], v[40:41], off
	v_add_co_u32_e32 v38, vcc, 0x4000, v50
	v_lshl_add_u64 v[52:53], v[112:113], 0, v[52:53]
	s_nop 0
	v_addc_co_u32_e32 v39, vcc, 0, v51, vcc
	v_add_co_u32_e32 v40, vcc, 0x5000, v50
	v_add_u32_e32 v186, 0x9000, v155
	s_nop 0
	v_addc_co_u32_e32 v41, vcc, 0, v51, vcc
	global_load_dwordx4 v[66:69], v[38:39], off
	global_load_dwordx4 v[62:65], v[40:41], off
	v_add_co_u32_e32 v38, vcc, 0x6000, v50
	v_add_u32_e32 v183, 0xd000, v155
	s_nop 0
	v_addc_co_u32_e32 v39, vcc, 0, v51, vcc
	v_add_co_u32_e32 v40, vcc, 0x7000, v50
	v_add_u32_e32 v184, 0x9000, v161
	s_nop 0
	v_addc_co_u32_e32 v41, vcc, 0, v51, vcc
	v_add_co_u32_e32 v42, vcc, 0x8000, v50
	global_load_dwordx4 v[58:61], v[38:39], off
	s_nop 0
	global_load_dwordx4 v[38:41], v[40:41], off
	v_addc_co_u32_e32 v43, vcc, 0, v51, vcc
	v_add_co_u32_e32 v44, vcc, 0x9000, v50
	v_add_u32_e32 v185, 0xd000, v161
	s_nop 0
	v_addc_co_u32_e32 v45, vcc, 0, v51, vcc
	v_add_co_u32_e32 v50, vcc, 0xa000, v50
	global_load_dwordx4 v[46:49], v[42:43], off
	s_nop 0
	global_load_dwordx4 v[42:45], v[44:45], off
	v_addc_co_u32_e32 v51, vcc, 0, v51, vcc
	global_load_dwordx4 v[54:57], v[50:51], off
	s_nop 0
	global_load_dwordx4 v[50:53], v[52:53], off
	s_waitcnt lgkmcnt(0)
	s_barrier
	ds_read_b128 v[118:121], v177
	ds_read_b32 v108, v155 offset:36992
	ds_read_b128 v[126:129], v177 offset:64
	s_waitcnt lgkmcnt(2)
	v_mfma_f32_16x16x32_bf16 v[122:125], v[118:121], v[2:5], 0
	v_mov_b32_e32 v187, v140
	s_waitcnt lgkmcnt(0)
	v_mfma_f32_16x16x32_bf16 v[122:125], v[126:129], v[14:17], v[122:125]
	v_mfma_f32_16x16x32_bf16 v[118:121], v[118:121], v[6:9], 0
	s_nop 6
	v_add_f32_e32 v122, v97, v122
	v_mul_f32_e32 v122, 0xbfb8aa3b, v122
	v_exp_f32_e32 v122, v122
	v_mfma_f32_16x16x32_bf16 v[118:121], v[126:129], v[10:13], v[118:121]
	ds_read2_b32 v[126:127], v186 offset1:16
	v_add_f32_e32 v123, v97, v123
	v_add_f32_e32 v122, 1.0, v122
	v_rcp_f32_e32 v122, v122
	v_mul_f32_e32 v123, 0xbfb8aa3b, v123
	s_nop 2
	v_add_f32_e32 v118, v93, v118
	v_mul_f32_e32 v118, 0xbfb8aa3b, v118
	v_mul_f32_e32 v122, 0xc1000000, v122
	v_mul_f32_e32 v122, v180, v122
	v_mul_f32_e32 v122, 0x3fb8aa3b, v122
	v_exp_f32_e32 v118, v118
	v_exp_f32_e32 v122, v122
	v_exp_f32_e32 v123, v123
	v_add_f32_e32 v119, v93, v119
	v_add_f32_e32 v118, 1.0, v118
	v_fma_f32 v128, -v122, v122, 1.0
	v_rcp_f32_e32 v118, v118
	v_max_f32_e32 v128, 0, v128
	v_sqrt_f32_e32 v128, v128
	v_mul_f32_e32 v119, 0xbfb8aa3b, v119
	s_waitcnt lgkmcnt(0)
	v_mul_f32_e32 v118, v126, v118
	v_exp_f32_e32 v119, v119
	v_mul_f32_e32 v118, v118, v128
	ds_write_b32 v156, v118
	v_add_f32_e32 v118, 1.0, v123
	v_rcp_f32_e32 v118, v118
	v_add_f32_e32 v124, v97, v124
	v_add_f32_e32 v119, 1.0, v119
	v_mul_f32_e32 v124, 0xbfb8aa3b, v124
	v_mul_f32_e32 v118, 0xc1000000, v118
	v_mul_f32_e32 v118, v180, v118
	v_mul_f32_e32 v118, 0x3fb8aa3b, v118
	v_exp_f32_e32 v118, v118
	v_rcp_f32_e32 v119, v119
	v_exp_f32_e32 v124, v124
	v_add_f32_e32 v120, v93, v120
	v_fma_f32 v123, -v118, v118, 1.0
	ds_write2_b32 v183, v122, v118 offset1:16
	v_mul_f32_e32 v118, v127, v119
	v_add_f32_e32 v119, 1.0, v124
	v_rcp_f32_e32 v119, v119
	v_max_f32_e32 v123, 0, v123
	v_sqrt_f32_e32 v123, v123
	v_mul_f32_e32 v120, 0xbfb8aa3b, v120
	v_mul_f32_e32 v119, 0xc1000000, v119
	v_mul_f32_e32 v119, v180, v119
	v_mul_f32_e32 v119, 0x3fb8aa3b, v119
	v_exp_f32_e32 v120, v120
	v_exp_f32_e32 v119, v119
	v_mul_f32_e32 v118, v118, v123
	ds_write_b32 v157, v118
	v_add_f32_e32 v118, 1.0, v120
	ds_write_b32 v155, v119 offset:53376
	v_fma_f32 v119, -v119, v119, 1.0
	v_rcp_f32_e32 v118, v118
	v_max_f32_e32 v119, 0, v119
	v_add_f32_e32 v120, v97, v125
	v_sqrt_f32_e32 v119, v119
	v_mul_f32_e32 v120, 0xbfb8aa3b, v120
	v_exp_f32_e32 v120, v120
	v_mul_f32_e32 v108, v118, v108
	v_mul_f32_e32 v108, v108, v119
	ds_write_b32 v158, v108
	v_add_f32_e32 v108, 1.0, v120
	v_rcp_f32_e32 v108, v108
	v_add_f32_e32 v118, v93, v121
	v_mul_f32_e32 v118, 0xbfb8aa3b, v118
	v_exp_f32_e32 v118, v118
	v_mul_f32_e32 v108, 0xc1000000, v108
	v_mul_f32_e32 v108, v180, v108
	v_mul_f32_e32 v108, 0x3fb8aa3b, v108
	v_exp_f32_e32 v108, v108
	ds_read_b32 v119, v159 offset:36864
	v_add_f32_e32 v118, 1.0, v118
	v_rcp_f32_e32 v118, v118
	v_fma_f32 v120, -v108, v108, 1.0
	v_max_f32_e32 v120, 0, v120
	v_sqrt_f32_e32 v120, v120
	ds_write_b32 v159, v108 offset:53248
	s_waitcnt lgkmcnt(1)
	v_mul_f32_e32 v108, v118, v119
	v_mul_f32_e32 v108, v108, v120
	ds_write_b32 v160, v108
	ds_read_b128 v[118:121], v178
	ds_read_b32 v108, v161 offset:36992
	ds_read_b128 v[126:129], v178 offset:64
	s_waitcnt lgkmcnt(2)
	v_mfma_f32_16x16x32_bf16 v[122:125], v[118:121], v[2:5], 0
	s_waitcnt lgkmcnt(0)
; #define LAS __attribute__((address_space(3)))
; __device__ __forceinline__ float fexp(float x) { return __builtin_amdgcn_exp2f(x * 1.44269504089f); }
; __device__ __forceinline__ float fsigmoid(float x) { return __builtin_amdgcn_rcpf(1.0f + fexp(-x)); }
; __device__ __forceinline__ void lru_item(const Args& a, LAS unsigned char* lds, bool sample, int b, int head, int q, int tid, int lane, int wave) {
;     ...
; #pragma unroll
;             for (int tt = 0; tt < 2; ++tt) {
;                 const int tile = 2 * wave + tt;
;                 f32x4 ar = (f32x4){0.f, 0.f, 0.f, 0.f}, ax = ar;
; #pragma unroll
;                 for (int ks = 0; ks < 2; ++ks) {
;                     const bf16x8 af = *(const LAS bf16x8*)(XC + (16 * tile + fr) * XC_PITCH + 64 * ks + 16 * fq);
;                     ar = __builtin_amdgcn_mfma_f32_16x16x32_bf16(af, Bf[0][ks], ar, 0, 0, 0);
;                     ax = __builtin_amdgcn_mfma_f32_16x16x32_bf16(af, Bf[1][ks], ax, 0, 0, 0);
;                 }
; #pragma unroll
;                 for (int r4 = 0; r4 < 4; ++r4) {
;                     const int rr = 16 * tile + 4 * fq + r4;
;                     const float xcv = XCF[rr * 16 + fr];
;                     const float rg_ = fsigmoid(ar[r4] + ba), ig = fsigmoid(ax[r4] + bx_);
;                     const float la = -8.0f * rg_ * spl;
;                     const float av = fexp(la); AA[rr * 16 + fr] = av; BX[rr * 16 + fr] = __builtin_amdgcn_sqrtf(fmaxf(fmaf(-av, av, 1.0f), 0.f)) * (ig * xcv);
;                 }
;             }
;             __syncthreads();
;             const int sn = tid & 15, sg = tid >> 4;
;             float av[8], bv[8];
;             const LAS float* ap = AA + (8 * sg) * 16 + sn; LAS float* bp = BX + (8 * sg) * 16 + sn;
;             asm volatile("" : "+v"(ap), "+v"(bp));
;             { float P = 1.f, h = 0.f;
; #pragma unroll
;               for (int i = 0; i < 8; ++i) { av[i] = ap[i * 16]; bv[i] = bp[i * 16]; }
; #pragma unroll
;               for (int i = 0; i < 8; ++i) { h = av[i] * h + bv[i]; P *= av[i]; }
;               SEGP[tid] = P; SEGH[tid] = h; }
;             __syncthreads();
	v_mfma_f32_16x16x32_bf16 v[122:125], v[126:129], v[14:17], v[122:125]
	v_mfma_f32_16x16x32_bf16 v[118:121], v[118:121], v[6:9], 0
	s_nop 6
	v_add_f32_e32 v122, v97, v122
	v_mul_f32_e32 v122, 0xbfb8aa3b, v122
	v_exp_f32_e32 v122, v122
	v_mfma_f32_16x16x32_bf16 v[118:121], v[126:129], v[10:13], v[118:121]
	ds_read2_b32 v[126:127], v184 offset1:16
	v_add_f32_e32 v123, v97, v123
	v_add_f32_e32 v122, 1.0, v122
	v_rcp_f32_e32 v122, v122
	v_mul_f32_e32 v123, 0xbfb8aa3b, v123
	s_nop 2
	v_add_f32_e32 v118, v93, v118
	v_mul_f32_e32 v118, 0xbfb8aa3b, v118
	v_mul_f32_e32 v122, 0xc1000000, v122
	v_mul_f32_e32 v122, v180, v122
	v_mul_f32_e32 v122, 0x3fb8aa3b, v122
	v_exp_f32_e32 v118, v118
	v_exp_f32_e32 v122, v122
	v_exp_f32_e32 v123, v123
	v_add_f32_e32 v119, v93, v119
	v_add_f32_e32 v118, 1.0, v118
	v_fma_f32 v128, -v122, v122, 1.0
	v_rcp_f32_e32 v118, v118
	v_max_f32_e32 v128, 0, v128
	v_sqrt_f32_e32 v128, v128
	v_mul_f32_e32 v119, 0xbfb8aa3b, v119
	s_waitcnt lgkmcnt(0)
	v_mul_f32_e32 v118, v126, v118
	v_exp_f32_e32 v119, v119
	v_mul_f32_e32 v118, v118, v128
	ds_write_b32 v164, v118
	v_add_f32_e32 v118, 1.0, v123
	v_rcp_f32_e32 v118, v118
	v_add_f32_e32 v124, v97, v124
	v_add_f32_e32 v119, 1.0, v119
	v_mul_f32_e32 v124, 0xbfb8aa3b, v124
	v_mul_f32_e32 v118, 0xc1000000, v118
	v_mul_f32_e32 v118, v180, v118
	v_mul_f32_e32 v118, 0x3fb8aa3b, v118
	v_exp_f32_e32 v118, v118
	v_rcp_f32_e32 v119, v119
	v_exp_f32_e32 v124, v124
	v_add_f32_e32 v120, v93, v120
	v_fma_f32 v123, -v118, v118, 1.0
	ds_write2_b32 v185, v122, v118 offset1:16
	v_mul_f32_e32 v118, v127, v119
	v_add_f32_e32 v119, 1.0, v124
	v_rcp_f32_e32 v119, v119
	v_max_f32_e32 v123, 0, v123
	v_sqrt_f32_e32 v123, v123
	v_mul_f32_e32 v120, 0xbfb8aa3b, v120
	v_mul_f32_e32 v119, 0xc1000000, v119
	v_mul_f32_e32 v119, v180, v119
	v_mul_f32_e32 v119, 0x3fb8aa3b, v119
	v_exp_f32_e32 v120, v120
	v_exp_f32_e32 v119, v119
	v_mul_f32_e32 v118, v118, v123
	ds_write_b32 v165, v118
	v_add_f32_e32 v118, 1.0, v120
	ds_write_b32 v161, v119 offset:53376
	v_fma_f32 v119, -v119, v119, 1.0
	v_rcp_f32_e32 v118, v118
	v_max_f32_e32 v119, 0, v119
	v_add_f32_e32 v120, v97, v125
	v_sqrt_f32_e32 v119, v119
	v_mul_f32_e32 v120, 0xbfb8aa3b, v120
	v_exp_f32_e32 v120, v120
	v_mul_f32_e32 v108, v118, v108
	v_mul_f32_e32 v108, v108, v119
	ds_write_b32 v166, v108
	v_add_f32_e32 v108, 1.0, v120
	v_rcp_f32_e32 v108, v108
	v_add_f32_e32 v118, v93, v121
	v_mul_f32_e32 v118, 0xbfb8aa3b, v118
	v_exp_f32_e32 v118, v118
	v_mul_f32_e32 v108, 0xc1000000, v108
	v_mul_f32_e32 v108, v180, v108
	v_mul_f32_e32 v108, 0x3fb8aa3b, v108
	v_exp_f32_e32 v108, v108
	ds_read_b32 v119, v167 offset:36864
	v_add_f32_e32 v118, 1.0, v118
	v_rcp_f32_e32 v118, v118
	v_fma_f32 v120, -v108, v108, 1.0
	v_max_f32_e32 v120, 0, v120
	v_sqrt_f32_e32 v120, v120
	ds_write_b32 v167, v108 offset:53248
	s_waitcnt lgkmcnt(1)
	v_mul_f32_e32 v108, v118, v119
	v_mul_f32_e32 v108, v108, v120
	ds_write_b32 v168, v108
	v_mov_b32_e32 v108, v139
	s_waitcnt lgkmcnt(0)
	s_barrier
	ds_read2_b32 v[132:133], v108 offset1:16
	ds_read2_b32 v[130:131], v187 offset1:16
	ds_read2_b32 v[128:129], v108 offset0:32 offset1:48
	ds_read2_b32 v[126:127], v187 offset0:32 offset1:48
	ds_read2_b32 v[124:125], v108 offset0:64 offset1:80
	ds_read2_b32 v[122:123], v187 offset0:64 offset1:80
	ds_read2_b32 v[118:119], v108 offset0:96 offset1:112
	ds_read2_b32 v[120:121], v187 offset0:96 offset1:112
	s_waitcnt lgkmcnt(6)
	v_fma_f32 v108, 0, v132, v130
	v_mul_f32_e32 v188, v132, v133
	v_fma_f32 v108, v108, v133, v131
	s_waitcnt lgkmcnt(5)
	v_mul_f32_e32 v188, v188, v128
	s_waitcnt lgkmcnt(4)
	v_fma_f32 v108, v108, v128, v126
	v_mul_f32_e32 v188, v188, v129
	v_fma_f32 v108, v108, v129, v127
	s_waitcnt lgkmcnt(3)
	v_mul_f32_e32 v188, v188, v124
	s_waitcnt lgkmcnt(2)
	v_fma_f32 v108, v108, v124, v122
	v_mul_f32_e32 v188, v188, v125
	v_fma_f32 v108, v108, v125, v123
	s_waitcnt lgkmcnt(1)
	v_mul_f32_e32 v188, v188, v118
	s_waitcnt lgkmcnt(0)
	v_fma_f32 v108, v108, v118, v120
	v_mul_f32_e32 v188, v188, v119
	v_fma_f32 v108, v108, v119, v121
	ds_write_b32 v141, v188
	ds_write_b32 v142, v108
	s_waitcnt lgkmcnt(0)
	s_barrier
	s_and_saveexec_b64 s[36:37], s[18:19]
	s_cbranch_execz .LBB0_690
; #define LAS __attribute__((address_space(3)))
; __device__ __forceinline__ void lru_item(const Args& a, LAS unsigned char* lds, bool sample, int b, int head, int q, int tid, int lane, int wave) {
;     ...
;             if (wave == 0 && lane < 16) {
;                 const LAS float* pp = SEGP + lane; const LAS float* hp = SEGH + lane; LAS float* cp = CAR + lane;
;                 asm volatile("" : "+v"(pp), "+v"(hp), "+v"(cp));
;                 float run = hcar;
; #pragma unroll
;                 for (int h2 = 0; h2 < 2; ++h2) {
;                     float sp_[16], sh_[16];
; #pragma unroll
;                     for (int s2 = 0; s2 < 16; ++s2) { sp_[s2] = pp[(16 * h2 + s2) * 16]; sh_[s2] = hp[(16 * h2 + s2) * 16]; }
; #pragma unroll
;                     for (int s2 = 0; s2 < 16; ++s2) { cp[(16 * h2 + s2) * 16] = run; run = sp_[s2] * run + sh_[s2]; }
;                 }
;                 hcar = run;
;             }
	v_mov_b32_e32 v108, v144
	v_mov_b32_e32 v211, v143
	v_mov_b32_e32 v222, v145
	ds_read2_b32 v[188:189], v211 offset1:16
	ds_read2_b32 v[190:191], v108 offset1:16
	ds_read2_b32 v[192:193], v211 offset0:32 offset1:48
	ds_read2_b32 v[194:195], v108 offset0:32 offset1:48
	ds_read2_b32 v[196:197], v211 offset0:64 offset1:80
	ds_read2_b32 v[198:199], v108 offset0:64 offset1:80
	ds_read2_b32 v[200:201], v211 offset0:96 offset1:112
	ds_read2_b32 v[202:203], v108 offset0:96 offset1:112
	ds_read2_b32 v[204:205], v211 offset0:128 offset1:144
	ds_read2_b32 v[206:207], v108 offset0:128 offset1:144
	ds_read2_b32 v[208:209], v211 offset0:160 offset1:176
	ds_read2_b32 v[212:213], v108 offset0:160 offset1:176
	ds_read2_b32 v[214:215], v211 offset0:192 offset1:208
	ds_read2_b32 v[216:217], v108 offset0:192 offset1:208
	ds_read2_b32 v[218:219], v211 offset0:224 offset1:240
	ds_read2_b32 v[220:221], v108 offset0:224 offset1:240
	s_waitcnt lgkmcnt(14)
	v_fma_f32 v188, v109, v188, v190
	v_fmac_f32_e32 v191, v188, v189
	ds_write2_b32 v222, v109, v188 offset1:16
	s_waitcnt lgkmcnt(13)
	v_fma_f32 v109, v191, v192, v194
	v_fmac_f32_e32 v195, v109, v193
	ds_write2_b32 v222, v191, v109 offset0:32 offset1:48
	s_waitcnt lgkmcnt(12)
	v_fma_f32 v109, v195, v196, v198
	v_fmac_f32_e32 v199, v109, v197
	ds_write2_b32 v222, v195, v109 offset0:64 offset1:80
	s_waitcnt lgkmcnt(11)
	v_fma_f32 v109, v199, v200, v202
	v_fmac_f32_e32 v203, v109, v201
	ds_write2_b32 v222, v199, v109 offset0:96 offset1:112
	s_waitcnt lgkmcnt(10)
	v_fma_f32 v109, v203, v204, v206
	v_fmac_f32_e32 v207, v109, v205
	ds_write2_b32 v222, v203, v109 offset0:128 offset1:144
	s_waitcnt lgkmcnt(9)
	v_fma_f32 v109, v207, v208, v212
	v_fmac_f32_e32 v213, v109, v209
	ds_write2_b32 v222, v207, v109 offset0:160 offset1:176
	s_waitcnt lgkmcnt(8)
	v_fma_f32 v109, v213, v214, v216
	v_fmac_f32_e32 v217, v109, v215
	ds_write2_b32 v222, v213, v109 offset0:192 offset1:208
	s_waitcnt lgkmcnt(7)
	v_fma_f32 v109, v217, v218, v220
	ds_write2_b32 v222, v217, v109 offset0:224 offset1:240
	v_fmac_f32_e32 v221, v109, v219
	v_add_u32_e32 v109, 0x400, v211
	ds_read2_b32 v[188:189], v109 offset1:16
	v_add_u32_e32 v108, 0x400, v108
	ds_read2_b32 v[190:191], v108 offset1:16
	ds_read2_b32 v[192:193], v109 offset0:32 offset1:48
	ds_read2_b32 v[194:195], v108 offset0:32 offset1:48
	ds_read2_b32 v[196:197], v109 offset0:64 offset1:80
	ds_read2_b32 v[198:199], v108 offset0:64 offset1:80
	ds_read2_b32 v[200:201], v109 offset0:96 offset1:112
	ds_read2_b32 v[202:203], v108 offset0:96 offset1:112
	ds_read2_b32 v[204:205], v109 offset0:128 offset1:144
	ds_read2_b32 v[206:207], v108 offset0:128 offset1:144
	ds_read2_b32 v[208:209], v109 offset0:160 offset1:176
	ds_read2_b32 v[212:213], v108 offset0:160 offset1:176
	ds_read2_b32 v[214:215], v109 offset0:192 offset1:208
	ds_read2_b32 v[216:217], v108 offset0:192 offset1:208
	ds_read2_b32 v[218:219], v109 offset0:224 offset1:240
	ds_read2_b32 v[108:109], v108 offset0:224 offset1:240
	s_waitcnt lgkmcnt(14)
	v_fma_f32 v188, v221, v188, v190
	v_add_u32_e32 v190, 0x400, v222
	v_fmac_f32_e32 v191, v188, v189
	ds_write2_b32 v190, v221, v188 offset1:16
	s_waitcnt lgkmcnt(13)
	v_fma_f32 v188, v191, v192, v194
	v_fmac_f32_e32 v195, v188, v193
	ds_write2_b32 v190, v191, v188 offset0:32 offset1:48
	s_waitcnt lgkmcnt(12)
	v_fma_f32 v188, v195, v196, v198
	v_fmac_f32_e32 v199, v188, v197
	ds_write2_b32 v190, v195, v188 offset0:64 offset1:80
	s_waitcnt lgkmcnt(11)
	v_fma_f32 v188, v199, v200, v202
	v_fmac_f32_e32 v203, v188, v201
	ds_write2_b32 v190, v199, v188 offset0:96 offset1:112
	s_waitcnt lgkmcnt(10)
	v_fma_f32 v188, v203, v204, v206
	v_fmac_f32_e32 v207, v188, v205
	ds_write2_b32 v190, v203, v188 offset0:128 offset1:144
	s_waitcnt lgkmcnt(9)
	v_fma_f32 v188, v207, v208, v212
	v_fmac_f32_e32 v213, v188, v209
	ds_write2_b32 v190, v207, v188 offset0:160 offset1:176
	s_waitcnt lgkmcnt(8)
	v_fma_f32 v188, v213, v214, v216
	v_fmac_f32_e32 v217, v188, v215
	s_waitcnt lgkmcnt(6)
	v_fma_f32 v108, v217, v218, v108
	v_fmac_f32_e32 v109, v108, v219
	ds_write2_b32 v190, v213, v188 offset0:192 offset1:208
	ds_write2_b32 v190, v217, v108 offset0:224 offset1:240

; #define LAS __attribute__((address_space(3)))
; __device__ __forceinline__ unsigned cvt_pk_bf16(float lo, float hi) { unsigned r; asm("v_cvt_pk_bf16_f32 %0, %1, %2" : "=v"(r) : "v"(lo), "v"(hi)); return r; }
; __device__ __forceinline__ void lru_item(const Args& a, LAS unsigned char* lds, bool sample, int b, int head, int q, int tid, int lane, int wave) {
;     ...
;         for (int chk = 0; chk < 8; ++chk) {
;             const int R0 = b * SEQ + chk * 256, r0 = rg * 8;
; #pragma unroll
;             for (int rr = 0; rr < 8; ++rr) {
;                 const f32x4 xc = cb + cw0 * xin[rr] + cw1 * xin[rr + 1] + cw2 * xin[rr + 2] + cw3 * xin[rr + 3];
;                 u32x2 w; w.x = cvt_pk_bf16(xc[0], xc[1]); w.y = cvt_pk_bf16(xc[2], xc[3]);
;                 *(LAS u32x2*)(XC + (r0 + rr) * XC_PITCH + 8 * cq) = w;
;                 if ((cq >> 2) == q) *(LAS f32x4*)(XCF + (r0 + rr) * 16 + 4 * (cq & 3)) = xc;
;             }
;             const u32x4 gw = ggn;
;             if (chk < 7) {
;                 const float* p = XL + (size_t)(R0 + 256 + r0 - 3) * DH + cch;
; #pragma unroll
;                 for (int i = 0; i < 11; ++i) xin[i] = *(const f32x4*)(p + (size_t)i * DH);
;                 ggn = *(const u32x4*)(GG + (size_t)(R0 + 256 + er) * DH + ch0 + 8 * eh);
;             }
;             __syncthreads();
.LBB0_692:
	s_or_b64 exec, exec, s[36:37]
	s_addk_i32 s30, 0x100
	v_lshl_add_u64 v[114:115], v[114:115], 0, s[40:41]
	s_cmpk_eq_i32 s30, 0x700
	v_lshl_add_u64 v[116:117], v[116:117], 0, s[42:43]
	s_cbranch_scc1 .LBB0_694
	s_waitcnt vmcnt(2) lgkmcnt(0)
	v_mov_b64_e32 v[76:77], v[52:53]
	v_mov_b64_e32 v[74:75], v[50:51]
	s_branch .LBB0_672
